# plus: NSA block-ranking loop reads the next importance score one iteration ahead (LDS latency hidden under the compare work)
# baseline (speedup 1.0000x reference)
; DI void nsa_attention(int L2, char* lds, int vcu, int G, int tid, int wave, int lane) {
;     ...
;             const int tk = lane >> 3, sub = lane & 7;
;             float v[8]; int cnt[8];
; #pragma unroll
;             for (int e = 0; e < 8; ++e) { v[e] = imp[tk * 64 + 8 * e + sub]; cnt[e] = 0; }
;             for (int J2 = 1; J2 <= qt - 2; ++J2) { const float x = imp[tk * 64 + J2];
; #pragma unroll
;                 for (int e = 0; e < 8; ++e) { const int J = 8 * e + sub; cnt[e] += (x > v[e] || (x == v[e] && J2 < J)) ? 1 : 0; } }
.LBB0_847:
	ds_read2_b32 v[26:27], v31 offset1:1
	v_cmp_lt_u32_e64 s[18:19], s4, v150
	v_cmp_lt_u32_e64 s[20:21], s3, v149
	s_add_i32 s5, s5, -2
	v_add_u32_e32 v31, 8, v31
	s_waitcnt lgkmcnt(0)
	v_cmp_eq_f32_e64 s[14:15], v26, v0
	v_cmp_eq_f32_e64 s[16:17], v27, v11
	v_cmp_gt_f32_e32 vcc, v27, v11
	v_cmp_gt_f32_e64 s[12:13], v26, v0
	s_and_b64 s[16:17], s[16:17], s[20:21]
	s_and_b64 s[14:15], s[14:15], s[18:19]
	s_or_b64 s[12:13], s[12:13], s[14:15]
	s_or_b64 vcc, vcc, s[16:17]
	v_addc_co_u32_e32 v47, vcc, 0, v47, vcc
	v_addc_co_u32_e64 v46, vcc, 0, v46, s[12:13]
	v_cmp_eq_f32_e64 s[14:15], v26, v10
	v_cmp_eq_f32_e64 s[16:17], v27, v13
	v_cmp_lt_u32_e64 s[18:19], s4, v154
	v_cmp_lt_u32_e64 s[20:21], s3, v151
	v_cmp_gt_f32_e32 vcc, v27, v13
	v_cmp_gt_f32_e64 s[12:13], v26, v10
	s_and_b64 s[16:17], s[16:17], s[20:21]
	s_and_b64 s[14:15], s[14:15], s[18:19]
	s_or_b64 s[12:13], s[12:13], s[14:15]
	s_or_b64 vcc, vcc, s[16:17]
	v_addc_co_u32_e32 v45, vcc, 0, v45, vcc
	v_addc_co_u32_e64 v44, vcc, 0, v44, s[12:13]
	v_cmp_eq_f32_e64 s[14:15], v26, v12
	v_cmp_eq_f32_e64 s[16:17], v27, v15
	v_cmp_lt_u32_e64 s[18:19], s4, v156
	v_cmp_lt_u32_e64 s[20:21], s3, v153
	v_cmp_gt_f32_e32 vcc, v27, v15
	v_cmp_gt_f32_e64 s[12:13], v26, v12
	s_and_b64 s[16:17], s[16:17], s[20:21]
	s_and_b64 s[14:15], s[14:15], s[18:19]
	s_or_b64 s[12:13], s[12:13], s[14:15]
	s_or_b64 vcc, vcc, s[16:17]
	v_addc_co_u32_e32 v43, vcc, 0, v43, vcc
	v_addc_co_u32_e64 v42, vcc, 0, v42, s[12:13]
	v_cmp_eq_f32_e64 s[14:15], v26, v14
	v_cmp_eq_f32_e64 s[16:17], v27, v17
	v_cmp_lt_u32_e64 s[18:19], s4, v158
	v_cmp_lt_u32_e64 s[20:21], s3, v155
	v_cmp_gt_f32_e32 vcc, v27, v17
	v_cmp_gt_f32_e64 s[12:13], v26, v14
	s_and_b64 s[16:17], s[16:17], s[20:21]
	s_and_b64 s[14:15], s[14:15], s[18:19]
	s_or_b64 s[12:13], s[12:13], s[14:15]
	s_or_b64 vcc, vcc, s[16:17]
	v_addc_co_u32_e32 v41, vcc, 0, v41, vcc
	v_addc_co_u32_e64 v40, vcc, 0, v40, s[12:13]
	v_cmp_eq_f32_e64 s[14:15], v26, v16
	v_cmp_eq_f32_e64 s[16:17], v27, v19
	v_cmp_lt_u32_e64 s[18:19], s4, v160
	v_cmp_lt_u32_e64 s[20:21], s3, v157
	v_cmp_gt_f32_e32 vcc, v27, v19
	v_cmp_gt_f32_e64 s[12:13], v26, v16
	s_and_b64 s[16:17], s[16:17], s[20:21]
	s_and_b64 s[14:15], s[14:15], s[18:19]
	s_or_b64 s[12:13], s[12:13], s[14:15]
	s_or_b64 vcc, vcc, s[16:17]
	v_addc_co_u32_e32 v39, vcc, 0, v39, vcc
	v_addc_co_u32_e64 v38, vcc, 0, v38, s[12:13]
	v_cmp_eq_f32_e64 s[14:15], v26, v18
	v_cmp_eq_f32_e64 s[16:17], v27, v21
	v_cmp_lt_u32_e64 s[18:19], s4, v162
	v_cmp_lt_u32_e64 s[20:21], s3, v159
	v_cmp_gt_f32_e32 vcc, v27, v21
	v_cmp_gt_f32_e64 s[12:13], v26, v18
	s_and_b64 s[16:17], s[16:17], s[20:21]
	s_and_b64 s[14:15], s[14:15], s[18:19]
	s_or_b64 s[12:13], s[12:13], s[14:15]
	s_or_b64 vcc, vcc, s[16:17]
	v_addc_co_u32_e32 v37, vcc, 0, v37, vcc
	v_addc_co_u32_e64 v36, vcc, 0, v36, s[12:13]
	v_cmp_eq_f32_e64 s[14:15], v26, v20
	v_cmp_eq_f32_e64 s[16:17], v27, v23
	v_cmp_lt_u32_e64 s[18:19], s4, v164
	v_cmp_lt_u32_e64 s[20:21], s3, v161
	v_cmp_gt_f32_e32 vcc, v27, v23
	v_cmp_gt_f32_e64 s[12:13], v26, v20
	s_and_b64 s[16:17], s[16:17], s[20:21]
	s_and_b64 s[14:15], s[14:15], s[18:19]
	s_or_b64 s[12:13], s[12:13], s[14:15]
	s_or_b64 vcc, vcc, s[16:17]
	v_addc_co_u32_e32 v35, vcc, 0, v35, vcc
	v_addc_co_u32_e64 v34, vcc, 0, v34, s[12:13]
	v_cmp_eq_f32_e64 s[14:15], v26, v22
	v_cmp_eq_f32_e64 s[16:17], v27, v25
	v_cmp_lt_u32_e64 s[18:19], s4, v166
	v_cmp_lt_u32_e64 s[20:21], s3, v163
	v_cmp_gt_f32_e32 vcc, v27, v25
	v_cmp_gt_f32_e64 s[12:13], v26, v22
	s_and_b64 s[16:17], s[16:17], s[20:21]
	s_and_b64 s[14:15], s[14:15], s[18:19]
	s_or_b64 s[12:13], s[12:13], s[14:15]
	s_or_b64 vcc, vcc, s[16:17]
	s_add_i32 s4, s4, 2
	s_add_i32 s3, s3, 2
	v_addc_co_u32_e32 v32, vcc, 0, v32, vcc
	v_addc_co_u32_e64 v30, vcc, 0, v30, s[12:13]
	s_cmp_lg_u32 s5, 0
	s_cbranch_scc1 .LBB0_847
	v_add_u32_e32 v14, v30, v32
	v_add_u32_e32 v15, v34, v35
	v_add_u32_e32 v16, v36, v37
	v_add_u32_e32 v18, v38, v39
	v_add_u32_e32 v19, v40, v41
	v_add_u32_e32 v20, v42, v43
	v_add_u32_e32 v21, v44, v45
	v_add_u32_e32 v22, v46, v47
	s_cmp_lg_u32 s29, s2
	s_mov_b64 s[2:3], -1
	s_cbranch_scc0 .LBB0_852
	s_or_b32 s2, s29, 1
	s_add_i32 s4, s91, -1
	v_lshl_add_u32 v26, s2, 2, v193
	v_mov_b32_e32 v0, v14
	v_mov_b32_e32 v10, v15
	v_mov_b32_e32 v11, v16
	v_mov_b32_e32 v12, v18
	v_mov_b32_e32 v13, v19
	v_mov_b32_e32 v17, v20
	v_mov_b32_e32 v23, v21
	v_mov_b32_e32 v25, v22
	ds_read_b32 v27, v26
	v_add_u32_e32 v26, 4, v26
.LBB0_850:
	ds_read_b32 v30, v26
	v_cmp_lt_u32_e64 s[14:15], s2, v150
	v_add_u32_e32 v26, 4, v26
	s_waitcnt lgkmcnt(1)
	v_cmp_eq_f32_e64 s[12:13], v27, v2
	v_cmp_gt_f32_e32 vcc, v27, v2
	s_and_b64 s[12:13], s[12:13], s[14:15]
	s_or_b64 vcc, vcc, s[12:13]
	v_addc_co_u32_e32 v25, vcc, 0, v25, vcc
	v_cmp_eq_f32_e64 s[12:13], v27, v3
	v_cmp_lt_u32_e64 s[14:15], s2, v154
	v_cmp_gt_f32_e32 vcc, v27, v3
	s_and_b64 s[12:13], s[12:13], s[14:15]
	s_or_b64 vcc, vcc, s[12:13]
	v_addc_co_u32_e32 v23, vcc, 0, v23, vcc
	v_cmp_eq_f32_e64 s[12:13], v27, v4
	v_cmp_lt_u32_e64 s[14:15], s2, v156
	v_cmp_gt_f32_e32 vcc, v27, v4
	s_and_b64 s[12:13], s[12:13], s[14:15]
	s_or_b64 vcc, vcc, s[12:13]
	v_addc_co_u32_e32 v17, vcc, 0, v17, vcc
	v_cmp_eq_f32_e64 s[12:13], v27, v5
	v_cmp_lt_u32_e64 s[14:15], s2, v158
	v_cmp_gt_f32_e32 vcc, v27, v5
	s_and_b64 s[12:13], s[12:13], s[14:15]
	s_or_b64 vcc, vcc, s[12:13]
	v_addc_co_u32_e32 v13, vcc, 0, v13, vcc
	v_cmp_eq_f32_e64 s[12:13], v27, v6
	v_cmp_lt_u32_e64 s[14:15], s2, v160
	v_cmp_gt_f32_e32 vcc, v27, v6
	s_and_b64 s[12:13], s[12:13], s[14:15]
	s_or_b64 vcc, vcc, s[12:13]
	v_addc_co_u32_e32 v12, vcc, 0, v12, vcc
	v_cmp_eq_f32_e64 s[12:13], v27, v7
	v_cmp_lt_u32_e64 s[14:15], s2, v162
	v_cmp_gt_f32_e32 vcc, v27, v7
	s_and_b64 s[12:13], s[12:13], s[14:15]
	s_or_b64 vcc, vcc, s[12:13]
	v_addc_co_u32_e32 v11, vcc, 0, v11, vcc
	v_cmp_eq_f32_e64 s[12:13], v27, v8
	v_cmp_lt_u32_e64 s[14:15], s2, v164
	v_cmp_gt_f32_e32 vcc, v27, v8
	s_and_b64 s[12:13], s[12:13], s[14:15]
	s_or_b64 vcc, vcc, s[12:13]
	v_addc_co_u32_e32 v10, vcc, 0, v10, vcc
	v_cmp_eq_f32_e64 s[12:13], v27, v9
	v_cmp_lt_u32_e64 s[14:15], s2, v166
	v_cmp_gt_f32_e32 vcc, v27, v9
	s_and_b64 s[12:13], s[12:13], s[14:15]
	s_or_b64 vcc, vcc, s[12:13]
	s_add_i32 s2, s2, 1
	v_addc_co_u32_e32 v0, vcc, 0, v0, vcc
	s_waitcnt lgkmcnt(0)
	v_mov_b32_e32 v27, v30
	s_cmp_eq_u32 s4, s2
	s_cbranch_scc0 .LBB0_850
	s_mov_b64 s[2:3], 0
	v_mov_b32_e32 v26, s4
